# GEMM0 K loop: the second block of each CU (block id >= 256) runs its MFMA body at priority 3, the first at 2 (static asymmetric priority between CU partners)
# speedup vs baseline: 1.0017x; 1.0003x over previous
.LBB0_374:
	s_movk_i32 vcc_lo, 7
	v_readlane_b32 s4, v209, 0
	s_nop 3
	s_lshr_b32 s4, s4, 8
.Lgq_c:
	ds_read_b128 v[114:117], v188 offset:16384
	ds_read_b128 v[118:121], v188 offset:16896
	ds_read_b128 v[156:159], v188 offset:20480
	ds_read_b128 v[160:163], v188 offset:20992
	ds_read_b128 v[122:125], v112
	ds_read_b128 v[126:129], v112 offset:2048
	s_waitcnt lgkmcnt(1)
	v_mfma_f32_16x16x32_bf16 v[66:69], v[114:117], v[122:125], v[66:69]
	s_setprio 2
	s_cmp_eq_u32 s4, 0
	s_cbranch_scc1 .Lpq_a0
	s_setprio 3
.Lpq_a0:
	global_load_dwordx4 v[62:65], v216, s[0:1] offset:256
	v_mfma_f32_16x16x32_bf16 v[58:61], v[118:121], v[122:125], v[58:61]
	s_waitcnt vmcnt(8)
	ds_write_b128 v110, v[224:227] offset:32768
	v_mfma_f32_16x16x32_bf16 v[54:57], v[156:159], v[122:125], v[54:57]
	v_mfma_f32_16x16x32_bf16 v[50:53], v[160:163], v[122:125], v[50:53]
	global_load_dwordx4 v[70:73], v217, s[0:1] offset:256
	s_waitcnt lgkmcnt(1)
	v_mfma_f32_16x16x32_bf16 v[46:49], v[114:117], v[126:129], v[46:49]
	ds_read_b128 v[180:183], v112 offset:4096
	ds_read_b128 v[184:187], v112 offset:6144
	v_mfma_f32_16x16x32_bf16 v[42:45], v[118:121], v[126:129], v[42:45]
	s_waitcnt vmcnt(8)
	ds_write_b128 v110, v[228:231] offset:36864
	v_mfma_f32_16x16x32_bf16 v[38:41], v[156:159], v[126:129], v[38:41]
	global_load_dwordx4 v[74:77], v218, s[0:1] offset:256
	v_mfma_f32_16x16x32_bf16 v[34:37], v[160:163], v[126:129], v[34:37]
	s_waitcnt lgkmcnt(2)
	v_mfma_f32_16x16x32_bf16 v[30:33], v[114:117], v[180:183], v[30:33]
	ds_read_b128 v[164:167], v189 offset:16384
	ds_read_b128 v[168:171], v189 offset:16896
	v_mfma_f32_16x16x32_bf16 v[26:29], v[118:121], v[180:183], v[26:29]
	global_load_dwordx4 v[78:81], v219, s[0:1] offset:256
	v_mfma_f32_16x16x32_bf16 v[22:25], v[156:159], v[180:183], v[22:25]
	ds_read_b128 v[172:175], v189 offset:20480
	ds_read_b128 v[176:179], v189 offset:20992
	v_mfma_f32_16x16x32_bf16 v[18:21], v[160:163], v[180:183], v[18:21]
	s_waitcnt vmcnt(9)
	ds_write_b128 v110, v[232:235] offset:40960
	s_waitcnt lgkmcnt(6)
	v_mfma_f32_16x16x32_bf16 v[14:17], v[114:117], v[184:187], v[14:17]
	ds_read_b128 v[122:125], v113
	ds_read_b128 v[126:129], v113 offset:2048
	v_mfma_f32_16x16x32_bf16 v[10:13], v[118:121], v[184:187], v[10:13]
	global_load_dwordx4 v[82:85], v216, s[6:7] offset:256
	v_mfma_f32_16x16x32_bf16 v[6:9], v[156:159], v[184:187], v[6:9]
	s_waitcnt vmcnt(9)
	ds_write_b128 v110, v[236:239] offset:45056
	v_mfma_f32_16x16x32_bf16 v[2:5], v[160:163], v[184:187], v[2:5]
	s_waitcnt lgkmcnt(2)
	v_mfma_f32_16x16x32_bf16 v[66:69], v[164:167], v[122:125], v[66:69]
	global_load_dwordx4 v[86:89], v217, s[6:7] offset:256
	v_mfma_f32_16x16x32_bf16 v[58:61], v[168:171], v[122:125], v[58:61]
	s_waitcnt vmcnt(9)
	ds_write_b128 v190, v[240:243] offset:49168
	v_mfma_f32_16x16x32_bf16 v[54:57], v[172:175], v[122:125], v[54:57]
	v_mfma_f32_16x16x32_bf16 v[50:53], v[176:179], v[122:125], v[50:53]
	global_load_dwordx4 v[90:93], v218, s[6:7] offset:256
	s_waitcnt lgkmcnt(2)
	v_mfma_f32_16x16x32_bf16 v[46:49], v[164:167], v[126:129], v[46:49]
	ds_read_b128 v[180:183], v113 offset:4096
	ds_read_b128 v[184:187], v113 offset:6144
	v_mfma_f32_16x16x32_bf16 v[42:45], v[168:171], v[126:129], v[42:45]
	s_waitcnt vmcnt(9)
	ds_write_b128 v190, v[244:247] offset:53264
	v_mfma_f32_16x16x32_bf16 v[38:41], v[172:175], v[126:129], v[38:41]
	global_load_dwordx4 v[94:97], v219, s[6:7] offset:256
	v_mfma_f32_16x16x32_bf16 v[34:37], v[176:179], v[126:129], v[34:37]
	s_waitcnt lgkmcnt(2)
	v_mfma_f32_16x16x32_bf16 v[30:33], v[164:167], v[180:183], v[30:33]
	s_waitcnt vmcnt(9)
	ds_write_b128 v190, v[248:251] offset:57360
	v_mfma_f32_16x16x32_bf16 v[26:29], v[168:171], v[180:183], v[26:29]
	v_mfma_f32_16x16x32_bf16 v[22:25], v[172:175], v[180:183], v[22:25]
	v_mfma_f32_16x16x32_bf16 v[18:21], v[176:179], v[180:183], v[18:21]
	s_waitcnt vmcnt(8)
	ds_write_b128 v190, v[252:255] offset:61456
	s_waitcnt lgkmcnt(3)
	v_mfma_f32_16x16x32_bf16 v[14:17], v[164:167], v[184:187], v[14:17]
	v_mfma_f32_16x16x32_bf16 v[10:13], v[168:171], v[184:187], v[10:13]
	v_mfma_f32_16x16x32_bf16 v[6:9], v[172:175], v[184:187], v[6:9]
	v_mfma_f32_16x16x32_bf16 v[2:5], v[176:179], v[184:187], v[2:5]
	s_setprio 0
	s_waitcnt lgkmcnt(0)
	s_barrier
	s_add_u32 s0, s0, 0x80
	s_addc_u32 s1, s1, 0
	s_add_u32 s6, s6, 0x80
	s_addc_u32 s7, s7, 0
	ds_read_b128 v[114:117], v188 offset:49168
	ds_read_b128 v[118:121], v188 offset:49680
	ds_read_b128 v[156:159], v188 offset:53264
	ds_read_b128 v[160:163], v188 offset:53776
	ds_read_b128 v[122:125], v112 offset:32768
	ds_read_b128 v[126:129], v112 offset:34816
	s_waitcnt lgkmcnt(1)
	v_mfma_f32_16x16x32_bf16 v[66:69], v[114:117], v[122:125], v[66:69]
	s_setprio 2
	s_cmp_eq_u32 s4, 0
	s_cbranch_scc1 .Lpq_a1
	s_setprio 3
.Lpq_a1:
	global_load_dwordx4 v[224:227], v216, s[0:1] offset:256
	v_mfma_f32_16x16x32_bf16 v[58:61], v[118:121], v[122:125], v[58:61]
	s_waitcnt vmcnt(8)
	ds_write_b128 v110, v[62:65]
	v_mfma_f32_16x16x32_bf16 v[54:57], v[156:159], v[122:125], v[54:57]
	v_mfma_f32_16x16x32_bf16 v[50:53], v[160:163], v[122:125], v[50:53]
	global_load_dwordx4 v[228:231], v217, s[0:1] offset:256
	s_waitcnt lgkmcnt(1)
	v_mfma_f32_16x16x32_bf16 v[46:49], v[114:117], v[126:129], v[46:49]
	ds_read_b128 v[180:183], v112 offset:36864
	ds_read_b128 v[184:187], v112 offset:38912
	v_mfma_f32_16x16x32_bf16 v[42:45], v[118:121], v[126:129], v[42:45]
	s_waitcnt vmcnt(8)
	ds_write_b128 v110, v[70:73] offset:4096
	v_mfma_f32_16x16x32_bf16 v[38:41], v[156:159], v[126:129], v[38:41]
	global_load_dwordx4 v[232:235], v218, s[0:1] offset:256
	v_mfma_f32_16x16x32_bf16 v[34:37], v[160:163], v[126:129], v[34:37]
	s_waitcnt lgkmcnt(2)
	v_mfma_f32_16x16x32_bf16 v[30:33], v[114:117], v[180:183], v[30:33]
	ds_read_b128 v[164:167], v189 offset:49168
	ds_read_b128 v[168:171], v189 offset:49680
	v_mfma_f32_16x16x32_bf16 v[26:29], v[118:121], v[180:183], v[26:29]
	global_load_dwordx4 v[236:239], v219, s[0:1] offset:256
	v_mfma_f32_16x16x32_bf16 v[22:25], v[156:159], v[180:183], v[22:25]
	ds_read_b128 v[172:175], v189 offset:53264
	ds_read_b128 v[176:179], v189 offset:53776
	v_mfma_f32_16x16x32_bf16 v[18:21], v[160:163], v[180:183], v[18:21]
	s_waitcnt vmcnt(9)
	ds_write_b128 v110, v[74:77] offset:8192
	s_waitcnt lgkmcnt(6)
	v_mfma_f32_16x16x32_bf16 v[14:17], v[114:117], v[184:187], v[14:17]
	ds_read_b128 v[122:125], v113 offset:32768
	ds_read_b128 v[126:129], v113 offset:34816
	v_mfma_f32_16x16x32_bf16 v[10:13], v[118:121], v[184:187], v[10:13]
	global_load_dwordx4 v[240:243], v216, s[6:7] offset:256
	v_mfma_f32_16x16x32_bf16 v[6:9], v[156:159], v[184:187], v[6:9]
	s_waitcnt vmcnt(9)
	ds_write_b128 v110, v[78:81] offset:12288
	v_mfma_f32_16x16x32_bf16 v[2:5], v[160:163], v[184:187], v[2:5]
	s_waitcnt lgkmcnt(2)
	v_mfma_f32_16x16x32_bf16 v[66:69], v[164:167], v[122:125], v[66:69]
	global_load_dwordx4 v[244:247], v217, s[6:7] offset:256
	v_mfma_f32_16x16x32_bf16 v[58:61], v[168:171], v[122:125], v[58:61]
	s_waitcnt vmcnt(9)
	ds_write_b128 v190, v[82:85] offset:16384
	v_mfma_f32_16x16x32_bf16 v[54:57], v[172:175], v[122:125], v[54:57]
	v_mfma_f32_16x16x32_bf16 v[50:53], v[176:179], v[122:125], v[50:53]
	global_load_dwordx4 v[248:251], v218, s[6:7] offset:256
	s_waitcnt lgkmcnt(2)
	v_mfma_f32_16x16x32_bf16 v[46:49], v[164:167], v[126:129], v[46:49]
	ds_read_b128 v[180:183], v113 offset:36864
	ds_read_b128 v[184:187], v113 offset:38912
	v_mfma_f32_16x16x32_bf16 v[42:45], v[168:171], v[126:129], v[42:45]
	s_waitcnt vmcnt(9)
	ds_write_b128 v190, v[86:89] offset:20480
	v_mfma_f32_16x16x32_bf16 v[38:41], v[172:175], v[126:129], v[38:41]
	global_load_dwordx4 v[252:255], v219, s[6:7] offset:256
	v_mfma_f32_16x16x32_bf16 v[34:37], v[176:179], v[126:129], v[34:37]
	s_waitcnt lgkmcnt(2)
	v_mfma_f32_16x16x32_bf16 v[30:33], v[164:167], v[180:183], v[30:33]
	s_waitcnt vmcnt(9)
	ds_write_b128 v190, v[90:93] offset:24576
	v_mfma_f32_16x16x32_bf16 v[26:29], v[168:171], v[180:183], v[26:29]
	v_mfma_f32_16x16x32_bf16 v[22:25], v[172:175], v[180:183], v[22:25]
	v_mfma_f32_16x16x32_bf16 v[18:21], v[176:179], v[180:183], v[18:21]
	s_waitcnt vmcnt(8)
	ds_write_b128 v190, v[94:97] offset:28672
	s_waitcnt lgkmcnt(3)
	v_mfma_f32_16x16x32_bf16 v[14:17], v[164:167], v[184:187], v[14:17]
	v_mfma_f32_16x16x32_bf16 v[10:13], v[168:171], v[184:187], v[10:13]
	v_mfma_f32_16x16x32_bf16 v[6:9], v[172:175], v[184:187], v[6:9]
	v_mfma_f32_16x16x32_bf16 v[2:5], v[176:179], v[184:187], v[2:5]
	s_setprio 0
	s_waitcnt lgkmcnt(0)
	s_barrier
	s_add_u32 s0, s0, 0x80
	s_addc_u32 s1, s1, 0
	s_add_u32 s6, s6, 0x80
	s_addc_u32 s7, s7, 0
	s_sub_i32 vcc_lo, vcc_lo, 1
	s_cmp_lg_u32 vcc_lo, 0
	s_cbranch_scc1 .Lgq_c
	ds_read_b128 v[114:117], v188 offset:16384
	ds_read_b128 v[118:121], v188 offset:16896
	ds_read_b128 v[156:159], v188 offset:20480
	ds_read_b128 v[160:163], v188 offset:20992
	ds_read_b128 v[122:125], v112
	ds_read_b128 v[126:129], v112 offset:2048
	s_waitcnt lgkmcnt(1)
	v_mfma_f32_16x16x32_bf16 v[66:69], v[114:117], v[122:125], v[66:69]
	s_setprio 2
	s_cmp_eq_u32 s4, 0
	s_cbranch_scc1 .Lpq_a2
	s_setprio 3
.Lpq_a2:
	v_mfma_f32_16x16x32_bf16 v[58:61], v[118:121], v[122:125], v[58:61]
	s_waitcnt vmcnt(7)
	ds_write_b128 v110, v[224:227] offset:32768
	v_mfma_f32_16x16x32_bf16 v[54:57], v[156:159], v[122:125], v[54:57]
	v_mfma_f32_16x16x32_bf16 v[50:53], v[160:163], v[122:125], v[50:53]
	s_waitcnt lgkmcnt(1)
	v_mfma_f32_16x16x32_bf16 v[46:49], v[114:117], v[126:129], v[46:49]
	ds_read_b128 v[180:183], v112 offset:4096
	ds_read_b128 v[184:187], v112 offset:6144
	v_mfma_f32_16x16x32_bf16 v[42:45], v[118:121], v[126:129], v[42:45]
	s_waitcnt vmcnt(6)
	ds_write_b128 v110, v[228:231] offset:36864
	v_mfma_f32_16x16x32_bf16 v[38:41], v[156:159], v[126:129], v[38:41]
	v_mfma_f32_16x16x32_bf16 v[34:37], v[160:163], v[126:129], v[34:37]
	s_waitcnt lgkmcnt(2)
	v_mfma_f32_16x16x32_bf16 v[30:33], v[114:117], v[180:183], v[30:33]
	ds_read_b128 v[164:167], v189 offset:16384
	ds_read_b128 v[168:171], v189 offset:16896
	v_mfma_f32_16x16x32_bf16 v[26:29], v[118:121], v[180:183], v[26:29]
	v_mfma_f32_16x16x32_bf16 v[22:25], v[156:159], v[180:183], v[22:25]
	ds_read_b128 v[172:175], v189 offset:20480
	ds_read_b128 v[176:179], v189 offset:20992
	v_mfma_f32_16x16x32_bf16 v[18:21], v[160:163], v[180:183], v[18:21]
	s_waitcnt vmcnt(5)
	ds_write_b128 v110, v[232:235] offset:40960
	s_waitcnt lgkmcnt(6)
	v_mfma_f32_16x16x32_bf16 v[14:17], v[114:117], v[184:187], v[14:17]
	ds_read_b128 v[122:125], v113
	ds_read_b128 v[126:129], v113 offset:2048
	v_mfma_f32_16x16x32_bf16 v[10:13], v[118:121], v[184:187], v[10:13]
	v_mfma_f32_16x16x32_bf16 v[6:9], v[156:159], v[184:187], v[6:9]
	s_waitcnt vmcnt(4)
	ds_write_b128 v110, v[236:239] offset:45056
	v_mfma_f32_16x16x32_bf16 v[2:5], v[160:163], v[184:187], v[2:5]
	s_waitcnt lgkmcnt(2)
	v_mfma_f32_16x16x32_bf16 v[66:69], v[164:167], v[122:125], v[66:69]
	v_mfma_f32_16x16x32_bf16 v[58:61], v[168:171], v[122:125], v[58:61]
	s_waitcnt vmcnt(3)
	ds_write_b128 v190, v[240:243] offset:49168
	v_mfma_f32_16x16x32_bf16 v[54:57], v[172:175], v[122:125], v[54:57]
	v_mfma_f32_16x16x32_bf16 v[50:53], v[176:179], v[122:125], v[50:53]
	s_waitcnt lgkmcnt(2)
	v_mfma_f32_16x16x32_bf16 v[46:49], v[164:167], v[126:129], v[46:49]
	ds_read_b128 v[180:183], v113 offset:4096
	ds_read_b128 v[184:187], v113 offset:6144
	v_mfma_f32_16x16x32_bf16 v[42:45], v[168:171], v[126:129], v[42:45]
	s_waitcnt vmcnt(2)
	ds_write_b128 v190, v[244:247] offset:53264
	v_mfma_f32_16x16x32_bf16 v[38:41], v[172:175], v[126:129], v[38:41]
	v_mfma_f32_16x16x32_bf16 v[34:37], v[176:179], v[126:129], v[34:37]
	s_waitcnt lgkmcnt(2)
	v_mfma_f32_16x16x32_bf16 v[30:33], v[164:167], v[180:183], v[30:33]
	s_waitcnt vmcnt(1)
	ds_write_b128 v190, v[248:251] offset:57360
	v_mfma_f32_16x16x32_bf16 v[26:29], v[168:171], v[180:183], v[26:29]
	v_mfma_f32_16x16x32_bf16 v[22:25], v[172:175], v[180:183], v[22:25]
	v_mfma_f32_16x16x32_bf16 v[18:21], v[176:179], v[180:183], v[18:21]
	s_waitcnt vmcnt(0)
	ds_write_b128 v190, v[252:255] offset:61456
	s_waitcnt lgkmcnt(3)
	v_mfma_f32_16x16x32_bf16 v[14:17], v[164:167], v[184:187], v[14:17]
	v_mfma_f32_16x16x32_bf16 v[10:13], v[168:171], v[184:187], v[10:13]
	v_mfma_f32_16x16x32_bf16 v[6:9], v[172:175], v[184:187], v[6:9]
	v_mfma_f32_16x16x32_bf16 v[2:5], v[176:179], v[184:187], v[2:5]
	s_waitcnt lgkmcnt(0)
	s_barrier
	ds_read_b128 v[114:117], v188 offset:49168
	ds_read_b128 v[118:121], v188 offset:49680
	ds_read_b128 v[156:159], v188 offset:53264
	ds_read_b128 v[160:163], v188 offset:53776
	ds_read_b128 v[122:125], v112 offset:32768
	ds_read_b128 v[126:129], v112 offset:34816
	s_waitcnt lgkmcnt(1)
	v_mfma_f32_16x16x32_bf16 v[66:69], v[114:117], v[122:125], v[66:69]
	s_setprio 2
	s_cmp_eq_u32 s4, 0
	s_cbranch_scc1 .Lpq_a3
	s_setprio 3
.Lpq_a3:
	v_mfma_f32_16x16x32_bf16 v[58:61], v[118:121], v[122:125], v[58:61]
	v_mfma_f32_16x16x32_bf16 v[54:57], v[156:159], v[122:125], v[54:57]
	v_mfma_f32_16x16x32_bf16 v[50:53], v[160:163], v[122:125], v[50:53]
	s_waitcnt lgkmcnt(0)
	v_mfma_f32_16x16x32_bf16 v[46:49], v[114:117], v[126:129], v[46:49]
	ds_read_b128 v[180:183], v112 offset:36864
	ds_read_b128 v[184:187], v112 offset:38912
	v_mfma_f32_16x16x32_bf16 v[42:45], v[118:121], v[126:129], v[42:45]
	v_mfma_f32_16x16x32_bf16 v[38:41], v[156:159], v[126:129], v[38:41]
	v_mfma_f32_16x16x32_bf16 v[34:37], v[160:163], v[126:129], v[34:37]
	s_waitcnt lgkmcnt(1)
	v_mfma_f32_16x16x32_bf16 v[30:33], v[114:117], v[180:183], v[30:33]
	ds_read_b128 v[164:167], v189 offset:49168
	ds_read_b128 v[168:171], v189 offset:49680
	v_mfma_f32_16x16x32_bf16 v[26:29], v[118:121], v[180:183], v[26:29]
	v_mfma_f32_16x16x32_bf16 v[22:25], v[156:159], v[180:183], v[22:25]
	ds_read_b128 v[172:175], v189 offset:53264
	ds_read_b128 v[176:179], v189 offset:53776
	v_mfma_f32_16x16x32_bf16 v[18:21], v[160:163], v[180:183], v[18:21]
	s_waitcnt lgkmcnt(4)
	v_mfma_f32_16x16x32_bf16 v[14:17], v[114:117], v[184:187], v[14:17]
	ds_read_b128 v[122:125], v113 offset:32768
	ds_read_b128 v[126:129], v113 offset:34816
	v_mfma_f32_16x16x32_bf16 v[10:13], v[118:121], v[184:187], v[10:13]
	v_mfma_f32_16x16x32_bf16 v[6:9], v[156:159], v[184:187], v[6:9]
	v_mfma_f32_16x16x32_bf16 v[2:5], v[160:163], v[184:187], v[2:5]
	s_waitcnt lgkmcnt(1)
	v_mfma_f32_16x16x32_bf16 v[66:69], v[164:167], v[122:125], v[66:69]
	v_mfma_f32_16x16x32_bf16 v[58:61], v[168:171], v[122:125], v[58:61]
	v_mfma_f32_16x16x32_bf16 v[54:57], v[172:175], v[122:125], v[54:57]
	v_mfma_f32_16x16x32_bf16 v[50:53], v[176:179], v[122:125], v[50:53]
	s_waitcnt lgkmcnt(0)
	v_mfma_f32_16x16x32_bf16 v[46:49], v[164:167], v[126:129], v[46:49]
	ds_read_b128 v[180:183], v113 offset:36864
	ds_read_b128 v[184:187], v113 offset:38912
	v_mfma_f32_16x16x32_bf16 v[42:45], v[168:171], v[126:129], v[42:45]
	v_mfma_f32_16x16x32_bf16 v[38:41], v[172:175], v[126:129], v[38:41]
	v_mfma_f32_16x16x32_bf16 v[34:37], v[176:179], v[126:129], v[34:37]
	s_waitcnt lgkmcnt(1)
	v_mfma_f32_16x16x32_bf16 v[30:33], v[164:167], v[180:183], v[30:33]
	v_mfma_f32_16x16x32_bf16 v[26:29], v[168:171], v[180:183], v[26:29]
	v_mfma_f32_16x16x32_bf16 v[22:25], v[172:175], v[180:183], v[22:25]
	v_mfma_f32_16x16x32_bf16 v[18:21], v[176:179], v[180:183], v[18:21]
	s_waitcnt lgkmcnt(0)
	v_mfma_f32_16x16x32_bf16 v[14:17], v[164:167], v[184:187], v[14:17]
	v_mfma_f32_16x16x32_bf16 v[10:13], v[168:171], v[184:187], v[10:13]
	v_mfma_f32_16x16x32_bf16 v[6:9], v[172:175], v[184:187], v[6:9]
	v_mfma_f32_16x16x32_bf16 v[2:5], v[176:179], v[184:187], v[2:5]
	s_setprio 0
	s_barrier
